# attention unit epilogue: the sixteen row-sum butterflies use DPP / permlane16 moves instead of ds_bpermute round trips (bit-identical sums); on top of v189
# baseline (speedup 1.0000x reference)
; __device__ __forceinline__ unsigned cvt_pk_bf16(float lo, float hi) { f32x2 v = {lo, hi}; bf16x2_t b = __builtin_convertvector(v, bf16x2_t); return __builtin_bit_cast(unsigned, b); }
; __device__ __forceinline__ float bf_lo(unsigned w) { return __uint_as_float(w << 16); }
; __device__ __forceinline__ float bf_hi(unsigned w) { return __uint_as_float(w & 0xffff0000u); }
; __device__ __forceinline__ int crow(int r, int hi) { return (r & 3) + 8 * (r >> 2) + 4 * hi; }
;     ...
;     if (hi == 0) li_l[r32] = l_reg; asm volatile("s_waitcnt lgkmcnt(0)" ::: "memory");
;     float rli[16];
; #pragma unroll
;     for (int r = 0; r < 16; ++r) rli[r] = __builtin_amdgcn_rcpf(li_l[crow(r, hi)]);
;     if (mp == 0) {
; #pragma unroll
;       for (int d0 = 0; d0 < 4; ++d0)
; #pragma unroll
;         for (int r = 0; r < 16; r += 2) stash[(d0 * 8 + (r >> 1)) * 64] = cvt_pk_bf16(o[d0][r] * rli[r], o[d0][r + 1] * rli[r + 1]);
;     } else {
;       float ss[16];
; #pragma unroll
;       for (int r = 0; r < 16; ++r) ss[r] = 0.f;
; #pragma unroll
;       for (int d0 = 0; d0 < 4; ++d0)
; #pragma unroll
;         for (int r = 0; r < 16; r += 2) { const unsigned w = stash[(d0 * 8 + (r >> 1)) * 64];
;           const float a0 = bf_lo(w) - lam * (o[d0][r] * rli[r]), a1 = bf_hi(w) - lam * (o[d0][r + 1] * rli[r + 1]);
;           o[d0][r] = a0; o[d0][r + 1] = a1; ss[r] += a0 * a0; ss[r + 1] += a1 * a1; }
.LBB0_690:
	s_or_b64 exec, exec, s[4:5]
	s_waitcnt lgkmcnt(0)
	v_add_u32_e32 v72, s19, v168
	ds_read_b128 v[64:67], v72
	ds_read_b128 v[68:71], v72 offset:32
	s_lshl_b32 s0, s18, 13
	s_add_i32 s18, s0, 0
	s_add_i32 s18, s18, 0x12800
	s_waitcnt lgkmcnt(1)
	v_rcp_f32_e32 v91, v64
	v_rcp_f32_e32 v92, v65
	v_rcp_f32_e32 v93, v66
	v_rcp_f32_e32 v94, v67
	ds_read_b128 v[64:67], v72 offset:64
	v_lshl_add_u32 v90, v169, 2, s18
	s_waitcnt lgkmcnt(1)
	v_rcp_f32_e32 v95, v68
	v_rcp_f32_e32 v96, v69
	v_rcp_f32_e32 v97, v70
	v_rcp_f32_e32 v98, v71
	ds_read_b128 v[68:71], v72 offset:96
	s_waitcnt lgkmcnt(1)
	v_rcp_f32_e32 v99, v64
	v_rcp_f32_e32 v100, v65
	ds_read2st64_b32 v[64:65], v90 offset1:1
	v_rcp_f32_e32 v101, v66
	v_mul_f32_e32 v48, v48, v91
	s_waitcnt lgkmcnt(1)
	v_rcp_f32_e32 v85, v71
	ds_read2st64_b32 v[72:73], v90 offset0:2 offset1:3
	ds_read2st64_b32 v[74:75], v90 offset0:4 offset1:5
	ds_read2st64_b32 v[76:77], v90 offset0:6 offset1:7
	s_waitcnt lgkmcnt(3)
	v_lshlrev_b32_e32 v66, 16, v64
	v_fma_f32 v71, -v163, v48, v66
	v_and_b32_e32 v48, 0xffff0000, v64
	v_mul_f32_e32 v49, v49, v92
	v_rcp_f32_e32 v86, v70
	v_fma_f32 v70, -v163, v49, v48
	v_lshlrev_b32_e32 v48, 16, v65
	v_mul_f32_e32 v49, v50, v93
	v_rcp_f32_e32 v104, v69
	v_fma_f32 v69, -v163, v49, v48
	v_and_b32_e32 v48, 0xffff0000, v65
	v_mul_f32_e32 v49, v51, v94
	v_rcp_f32_e32 v103, v68
	v_fma_f32 v68, -v163, v49, v48
	s_waitcnt lgkmcnt(2)
	v_lshlrev_b32_e32 v48, 16, v72
	v_mul_f32_e32 v49, v52, v95
	v_rcp_f32_e32 v102, v67
	v_fma_f32 v67, -v163, v49, v48
	v_and_b32_e32 v48, 0xffff0000, v72
	v_mul_f32_e32 v49, v53, v96
	v_fma_f32 v66, -v163, v49, v48
	v_lshlrev_b32_e32 v48, 16, v73
	v_mul_f32_e32 v49, v54, v97
	v_fma_f32 v65, -v163, v49, v48
	v_and_b32_e32 v48, 0xffff0000, v73
	v_mul_f32_e32 v49, v55, v98
	v_fma_f32 v64, -v163, v49, v48
	s_waitcnt lgkmcnt(1)
	v_lshlrev_b32_e32 v48, 16, v74
	v_mul_f32_e32 v49, v56, v99
	v_fma_f32 v55, -v163, v49, v48
	v_and_b32_e32 v48, 0xffff0000, v74
	v_mul_f32_e32 v49, v57, v100
	v_fma_f32 v54, -v163, v49, v48
	v_lshlrev_b32_e32 v48, 16, v75
	v_mul_f32_e32 v49, v58, v101
	v_fma_f32 v53, -v163, v49, v48
	v_and_b32_e32 v48, 0xffff0000, v75
	v_mul_f32_e32 v49, v59, v102
	ds_read2st64_b32 v[58:59], v90 offset0:8 offset1:9
	v_fma_f32 v52, -v163, v49, v48
	s_waitcnt lgkmcnt(1)
	v_lshlrev_b32_e32 v48, 16, v76
	v_mul_f32_e32 v49, v60, v103
	v_fma_f32 v51, -v163, v49, v48
	v_and_b32_e32 v48, 0xffff0000, v76
	v_mul_f32_e32 v49, v61, v104
	v_fma_f32 v49, -v163, v49, v48
	v_lshlrev_b32_e32 v48, 16, v77
	v_mul_f32_e32 v50, v62, v86
	v_fma_f32 v48, -v163, v50, v48
	v_and_b32_e32 v50, 0xffff0000, v77
	v_mul_f32_e32 v56, v63, v85
	v_fma_f32 v50, -v163, v56, v50
	s_waitcnt lgkmcnt(0)
	v_lshlrev_b32_e32 v56, 16, v58
	v_mul_f32_e32 v32, v32, v91
	ds_read2st64_b32 v[60:61], v90 offset0:10 offset1:11
	ds_read2st64_b32 v[62:63], v90 offset0:12 offset1:13
	ds_read2st64_b32 v[76:77], v90 offset0:14 offset1:15
	v_fma_f32 v56, -v163, v32, v56
	v_and_b32_e32 v32, 0xffff0000, v58
	v_mul_f32_e32 v33, v33, v92
	v_fma_f32 v32, -v163, v33, v32
	v_lshlrev_b32_e32 v33, 16, v59
	v_mul_f32_e32 v34, v34, v93
	v_fma_f32 v34, -v163, v34, v33
	v_and_b32_e32 v33, 0xffff0000, v59
	v_mul_f32_e32 v35, v35, v94
	v_fma_f32 v33, -v163, v35, v33
	s_waitcnt lgkmcnt(2)
	v_lshlrev_b32_e32 v35, 16, v60
	v_mul_f32_e32 v36, v36, v95
	v_fma_f32 v36, -v163, v36, v35
	v_and_b32_e32 v35, 0xffff0000, v60
	v_mul_f32_e32 v37, v37, v96
	v_fma_f32 v35, -v163, v37, v35
	v_lshlrev_b32_e32 v37, 16, v61
	v_mul_f32_e32 v38, v38, v97
	v_fma_f32 v38, -v163, v38, v37
	v_and_b32_e32 v37, 0xffff0000, v61
	v_mul_f32_e32 v39, v39, v98
	v_fma_f32 v37, -v163, v39, v37
	s_waitcnt lgkmcnt(1)
	v_lshlrev_b32_e32 v39, 16, v62
	v_mul_f32_e32 v40, v40, v99
	v_fma_f32 v40, -v163, v40, v39
	v_and_b32_e32 v39, 0xffff0000, v62
	v_mul_f32_e32 v41, v41, v100
	v_fma_f32 v39, -v163, v41, v39
	v_lshlrev_b32_e32 v41, 16, v63
	v_mul_f32_e32 v42, v42, v101
	v_fma_f32 v42, -v163, v42, v41
	v_and_b32_e32 v41, 0xffff0000, v63
	v_mul_f32_e32 v43, v43, v102
	ds_read2st64_b32 v[58:59], v90 offset0:16 offset1:17
	v_fma_f32 v41, -v163, v43, v41
	s_waitcnt lgkmcnt(1)
	v_lshlrev_b32_e32 v43, 16, v76
	v_mul_f32_e32 v44, v44, v103
	v_fma_f32 v44, -v163, v44, v43
	v_and_b32_e32 v43, 0xffff0000, v76
	v_mul_f32_e32 v45, v45, v104
	v_fma_f32 v43, -v163, v45, v43
	v_lshlrev_b32_e32 v45, 16, v77
	v_mul_f32_e32 v46, v46, v86
	v_fma_f32 v46, -v163, v46, v45
	v_and_b32_e32 v45, 0xffff0000, v77
	v_mul_f32_e32 v47, v47, v85
	v_fma_f32 v45, -v163, v47, v45
	s_waitcnt lgkmcnt(0)
	v_lshlrev_b32_e32 v47, 16, v58
	v_mul_f32_e32 v16, v16, v91
	ds_read2st64_b32 v[76:77], v90 offset0:18 offset1:19
	ds_read2st64_b32 v[78:79], v90 offset0:20 offset1:21
	ds_read2st64_b32 v[88:89], v90 offset0:22 offset1:23
	v_fma_f32 v47, -v163, v16, v47
	v_and_b32_e32 v16, 0xffff0000, v58
	v_mul_f32_e32 v17, v17, v92
	v_fma_f32 v16, -v163, v17, v16
	v_lshlrev_b32_e32 v17, 16, v59
	v_mul_f32_e32 v18, v18, v93
	v_fma_f32 v57, -v163, v18, v17
	v_and_b32_e32 v17, 0xffff0000, v59
	v_mul_f32_e32 v18, v19, v94
	v_fma_f32 v17, -v163, v18, v17
	s_waitcnt lgkmcnt(2)
	v_lshlrev_b32_e32 v18, 16, v76
	v_mul_f32_e32 v19, v20, v95
	v_fma_f32 v58, -v163, v19, v18
	v_and_b32_e32 v18, 0xffff0000, v76
	v_mul_f32_e32 v19, v21, v96
	v_fma_f32 v18, -v163, v19, v18
	v_lshlrev_b32_e32 v19, 16, v77
	v_mul_f32_e32 v20, v22, v97
	v_fma_f32 v59, -v163, v20, v19
	v_and_b32_e32 v19, 0xffff0000, v77
	v_mul_f32_e32 v20, v23, v98
	v_fma_f32 v19, -v163, v20, v19
	s_waitcnt lgkmcnt(1)
; __device__ __forceinline__ float bf_lo(unsigned w) { return __uint_as_float(w << 16); }
; __device__ __forceinline__ float bf_hi(unsigned w) { return __uint_as_float(w & 0xffff0000u); }
;     ...
;         for (int r = 0; r < 16; r += 2) { const unsigned w = stash[(d0 * 8 + (r >> 1)) * 64];
;           const float a0 = bf_lo(w) - lam * (o[d0][r] * rli[r]), a1 = bf_hi(w) - lam * (o[d0][r + 1] * rli[r + 1]);
;           o[d0][r] = a0; o[d0][r + 1] = a1; ss[r] += a0 * a0; ss[r + 1] += a1 * a1; }
; #pragma unroll
;       for (int r = 0; r < 16; ++r) { float s = ss[r];
;         s += __shfl_xor(s, 1); s += __shfl_xor(s, 2); s += __shfl_xor(s, 4); s += __shfl_xor(s, 8); s += __shfl_xor(s, 16);
;         ss[r] = (1.0f - LAM_INIT) / sqrtf(s * (1.0f / 128.0f) + EPS); }
	v_lshlrev_b32_e32 v20, 16, v78
	v_mul_f32_e32 v21, v24, v99
	v_fma_f32 v23, -v163, v21, v20
	v_and_b32_e32 v20, 0xffff0000, v78
	v_mul_f32_e32 v21, v25, v100
	v_fma_f32 v20, -v163, v21, v20
	v_lshlrev_b32_e32 v21, 16, v79
	v_mul_f32_e32 v22, v26, v101
	v_fma_f32 v24, -v163, v22, v21
	v_and_b32_e32 v21, 0xffff0000, v79
	v_mul_f32_e32 v22, v27, v102
	v_mul_f32_e32 v25, v28, v103
	v_mul_f32_e32 v27, v30, v86
	v_mul_f32_e32 v28, v31, v85
	ds_read2st64_b32 v[30:31], v90 offset0:24 offset1:25
	v_fma_f32 v21, -v163, v22, v21
	s_waitcnt lgkmcnt(1)
	v_lshlrev_b32_e32 v22, 16, v88
	v_fma_f32 v25, -v163, v25, v22
	v_and_b32_e32 v22, 0xffff0000, v88
	v_mul_f32_e32 v26, v29, v104
	v_fma_f32 v22, -v163, v26, v22
	v_lshlrev_b32_e32 v26, 16, v89
	v_fma_f32 v27, -v163, v27, v26
	v_and_b32_e32 v26, 0xffff0000, v89
	v_fma_f32 v26, -v163, v28, v26
	s_waitcnt lgkmcnt(0)
	v_lshlrev_b32_e32 v28, 16, v30
	v_mul_f32_e32 v0, v0, v91
	ds_read2st64_b32 v[76:77], v90 offset0:26 offset1:27
	ds_read2st64_b32 v[78:79], v90 offset0:28 offset1:29
	ds_read2st64_b32 v[88:89], v90 offset0:30 offset1:31
	v_fma_f32 v28, -v163, v0, v28
	v_and_b32_e32 v0, 0xffff0000, v30
	v_mul_f32_e32 v1, v1, v92
	v_fma_f32 v0, -v163, v1, v0
	v_lshlrev_b32_e32 v1, 16, v31
	v_mul_f32_e32 v2, v2, v93
	v_fma_f32 v29, -v163, v2, v1
	v_and_b32_e32 v1, 0xffff0000, v31
	v_mul_f32_e32 v2, v3, v94
	v_fma_f32 v1, -v163, v2, v1
	s_waitcnt lgkmcnt(2)
	v_lshlrev_b32_e32 v2, 16, v76
	v_mul_f32_e32 v3, v4, v95
	v_fma_f32 v30, -v163, v3, v2
	v_and_b32_e32 v2, 0xffff0000, v76
	v_mul_f32_e32 v3, v5, v96
	v_fma_f32 v2, -v163, v3, v2
	v_lshlrev_b32_e32 v3, 16, v77
	v_mul_f32_e32 v4, v6, v97
	v_fma_f32 v31, -v163, v4, v3
	v_and_b32_e32 v3, 0xffff0000, v77
	v_mul_f32_e32 v4, v7, v98
	v_fma_f32 v3, -v163, v4, v3
	s_waitcnt lgkmcnt(1)
	v_lshlrev_b32_e32 v4, 16, v78
	v_mul_f32_e32 v5, v8, v99
	v_fma_f32 v7, -v163, v5, v4
	v_and_b32_e32 v4, 0xffff0000, v78
	v_mul_f32_e32 v5, v9, v100
	v_fma_f32 v4, -v163, v5, v4
	v_lshlrev_b32_e32 v5, 16, v79
	v_mul_f32_e32 v6, v10, v101
	v_fma_f32 v8, -v163, v6, v5
	v_and_b32_e32 v5, 0xffff0000, v79
	v_mul_f32_e32 v6, v11, v102
	v_fma_f32 v5, -v163, v6, v5
	s_waitcnt lgkmcnt(0)
	v_lshlrev_b32_e32 v6, 16, v88
	v_mul_f32_e32 v9, v12, v103
	v_fma_f32 v9, -v163, v9, v6
	v_and_b32_e32 v6, 0xffff0000, v88
	v_mul_f32_e32 v10, v13, v104
	v_and_b32_e32 v11, 64, v176
	v_mul_f32_e32 v105, v56, v56
	v_fma_f32 v6, -v163, v10, v6
	v_xor_b32_e32 v10, 1, v176
	v_add_u32_e32 v11, 64, v11
	v_fmac_f32_e32 v105, v71, v71
	v_cmp_lt_i32_e32 vcc, v10, v11
	v_fmac_f32_e32 v105, v47, v47
	v_fmac_f32_e32 v105, v28, v28
	v_cndmask_b32_e32 v10, v176, v10, vcc
	v_lshlrev_b32_e32 v73, 2, v10
	s_mov_b32 s98, 0xffff
	s_mov_b32 s99, 0xffff
	s_nop 1
	v_mov_b32_dpp v10, v105 quad_perm:[1,0,3,2] row_mask:0xf bank_mask:0xf
	v_xor_b32_e32 v12, 2, v176
	v_cmp_lt_i32_e32 vcc, v12, v11
	v_xor_b32_e32 v13, 4, v176
	v_mul_f32_e32 v106, v32, v32
	v_cndmask_b32_e32 v12, v176, v12, vcc
	v_lshlrev_b32_e32 v76, 2, v12
	s_waitcnt lgkmcnt(0)
	v_add_f32_e32 v10, v105, v10
	s_nop 1
	v_mov_b32_dpp v12, v10 quad_perm:[2,3,0,1] row_mask:0xf bank_mask:0xf
	v_cmp_lt_i32_e32 vcc, v13, v11
	v_fmac_f32_e32 v106, v70, v70
	v_fmac_f32_e32 v106, v16, v16
	v_cndmask_b32_e32 v13, v176, v13, vcc
	v_lshlrev_b32_e32 v77, 2, v13
	s_waitcnt lgkmcnt(0)
	v_add_f32_e32 v10, v10, v12
	s_nop 1
	v_mov_b32_dpp v12, v10 row_half_mirror row_mask:0xf bank_mask:0xf
	v_xor_b32_e32 v13, 8, v176
	v_cmp_lt_i32_e32 vcc, v13, v11
	v_fmac_f32_e32 v106, v0, v0
	v_mul_f32_e32 v107, v34, v34
	v_cndmask_b32_e32 v13, v176, v13, vcc
	v_lshlrev_b32_e32 v78, 2, v13
	s_waitcnt lgkmcnt(0)
	v_add_f32_e32 v10, v10, v12
	s_nop 1
	v_mov_b32_dpp v12, v10 row_mirror row_mask:0xf bank_mask:0xf
	v_xor_b32_e32 v13, 16, v176
	v_cmp_lt_i32_e32 vcc, v13, v11
	v_fmac_f32_e32 v107, v69, v69
	v_fmac_f32_e32 v107, v57, v57
	v_cndmask_b32_e32 v11, v176, v13, vcc
	v_lshlrev_b32_e32 v79, 2, v11
	s_waitcnt lgkmcnt(0)
	v_add_f32_e32 v10, v10, v12
	v_mov_b32_e32 v11, v10
	v_mov_b32_e32 v228, v10
	s_nop 1
	v_permlane16_swap_b32_e32 v11, v228
	s_nop 1
	v_cndmask_b32_e64 v11, v11, v228, s[98:99]
	v_mul_f32_e32 v13, v14, v86
	s_nop 1
	v_mov_b32_dpp v86, v106 quad_perm:[1,0,3,2] row_mask:0xf bank_mask:0xf
	v_lshlrev_b32_e32 v12, 16, v89
	v_fmac_f32_e32 v107, v29, v29
	s_waitcnt lgkmcnt(1)
	v_add_f32_e32 v10, v10, v11
	v_fmamk_f32 v10, v10, 0x3c000000, v165
	v_mul_f32_e32 v11, 0x4f800000, v10
	v_cmp_gt_f32_e32 vcc, s73, v10
	s_waitcnt lgkmcnt(0)
	v_add_f32_e32 v86, v106, v86
	s_nop 1
	v_mov_b32_dpp v88, v86 quad_perm:[2,3,0,1] row_mask:0xf bank_mask:0xf
	v_cndmask_b32_e32 v11, v10, v11, vcc
	v_sqrt_f32_e32 v14, v11
	v_fma_f32 v10, -v163, v13, v12
	v_mul_f32_e32 v13, v15, v85
	v_and_b32_e32 v12, 0xffff0000, v89
	v_add_u32_e32 v15, -1, v14
	v_fma_f32 v85, -v15, v14, v11
	v_cmp_ge_f32_e64 s[0:1], 0, v85
	v_add_u32_e32 v85, 1, v14
	s_nop 1
	v_mov_b32_dpp v90, v107 quad_perm:[1,0,3,2] row_mask:0xf bank_mask:0xf
	v_cndmask_b32_e64 v15, v14, v15, s[0:1]
	v_fma_f32 v14, -v85, v14, v11
	v_cmp_lt_f32_e64 s[0:1], 0, v14
	v_mul_f32_e32 v87, v33, v33
	s_waitcnt lgkmcnt(0)
	v_add_f32_e32 v90, v107, v90
	v_cndmask_b32_e64 v14, v15, v85, s[0:1]
	v_mul_f32_e32 v15, 0x37800000, v14
	v_cndmask_b32_e32 v14, v14, v15, vcc
	v_add_f32_e32 v15, v86, v88
	s_nop 1
	v_mov_b32_dpp v85, v15 row_half_mirror row_mask:0xf bank_mask:0xf
	v_cmp_class_f32_e32 vcc, v11, v175
	s_nop 1
	v_mov_b32_dpp v91, v90 quad_perm:[2,3,0,1] row_mask:0xf bank_mask:0xf
	v_fmac_f32_e32 v87, v68, v68
	v_cndmask_b32_e32 v14, v14, v11, vcc
	s_waitcnt lgkmcnt(1)
;     ...
;       for (int r = 0; r < 16; ++r) { float s = ss[r];
;         s += __shfl_xor(s, 1); s += __shfl_xor(s, 2); s += __shfl_xor(s, 4); s += __shfl_xor(s, 8); s += __shfl_xor(s, 16);
;         ss[r] = (1.0f - LAM_INIT) / sqrtf(s * (1.0f / 128.0f) + EPS); }
	v_add_f32_e32 v15, v15, v85
	s_nop 1
	v_mov_b32_dpp v85, v15 row_mirror row_mask:0xf bank_mask:0xf
	v_fma_f32 v11, -v163, v13, v12
	v_div_scale_f32 v86, s[0:1], v14, v14, s74
	v_rcp_f32_e32 v88, v86
	s_waitcnt lgkmcnt(0)
	v_add_f32_e32 v13, v15, v85
	v_mov_b32_e32 v15, v13
	v_mov_b32_e32 v228, v13
	s_nop 1
	v_permlane16_swap_b32_e32 v15, v228
	s_nop 1
	v_cndmask_b32_e64 v15, v15, v228, s[98:99]
	v_fmac_f32_e32 v87, v17, v17
	v_fma_f32 v12, -v86, v88, 1.0
	v_fmac_f32_e32 v88, v12, v88
	v_div_scale_f32 v12, vcc, s74, v14, s74
	s_waitcnt lgkmcnt(0)
	v_add_f32_e32 v13, v13, v15
	v_fmamk_f32 v13, v13, 0x3c000000, v165
	v_mul_f32_e32 v15, 0x4f800000, v13
	v_cmp_gt_f32_e64 s[0:1], s73, v13
	v_mul_f32_e32 v85, v12, v88
	v_fma_f32 v89, -v86, v85, v12
	v_cndmask_b32_e64 v13, v13, v15, s[0:1]
	v_sqrt_f32_e32 v15, v13
	v_fmac_f32_e32 v85, v89, v88
	v_fma_f32 v12, -v86, v85, v12
	v_div_fmas_f32 v12, v12, v88, v85
	v_add_u32_e32 v86, -1, v15
	v_fma_f32 v89, -v86, v15, v13
	v_cmp_ge_f32_e64 s[4:5], 0, v89
	v_add_u32_e32 v89, 1, v15
	v_fmac_f32_e32 v87, v1, v1
	v_cndmask_b32_e64 v86, v15, v86, s[4:5]
	v_fma_f32 v15, -v89, v15, v13
	v_cmp_lt_f32_e64 s[4:5], 0, v15
	v_div_fixup_f32 v12, v12, v14, s74
	v_mul_f32_e32 v84, v36, v36
	v_cndmask_b32_e64 v15, v86, v89, s[4:5]
	v_mul_f32_e32 v86, 0x37800000, v15
	v_cndmask_b32_e64 v15, v15, v86, s[0:1]
	v_add_f32_e32 v86, v90, v91
	s_nop 1
	v_mov_b32_dpp v89, v86 row_half_mirror row_mask:0xf bank_mask:0xf
	v_cmp_class_f32_e64 s[0:1], v13, v175
	s_nop 1
	v_mov_b32_dpp v91, v87 quad_perm:[1,0,3,2] row_mask:0xf bank_mask:0xf
	v_fmac_f32_e32 v84, v67, v67
	v_cndmask_b32_e64 v13, v15, v13, s[0:1]
	s_waitcnt lgkmcnt(1)
	v_add_f32_e32 v86, v86, v89
	s_nop 1
	v_mov_b32_dpp v89, v86 row_mirror row_mask:0xf bank_mask:0xf
	v_div_scale_f32 v15, s[0:1], v13, v13, s74
	v_rcp_f32_e32 v90, v15
	s_waitcnt lgkmcnt(1)
	v_add_f32_e32 v87, v87, v91
	s_waitcnt lgkmcnt(0)
	v_add_f32_e32 v85, v86, v89
	v_mov_b32_e32 v86, v85
	v_mov_b32_e32 v228, v85
	s_nop 1
	v_permlane16_swap_b32_e32 v86, v228
	s_nop 1
	v_cndmask_b32_e64 v86, v86, v228, s[98:99]
	v_fma_f32 v14, -v15, v90, 1.0
	v_fmac_f32_e32 v90, v14, v90
	v_div_scale_f32 v14, vcc, s74, v13, s74
	s_waitcnt lgkmcnt(0)
	v_add_f32_e32 v85, v85, v86
	v_fmamk_f32 v85, v85, 0x3c000000, v165
	v_mul_f32_e32 v86, 0x4f800000, v85
	v_cmp_gt_f32_e64 s[0:1], s73, v85
	v_mul_f32_e32 v88, v14, v90
	v_fma_f32 v89, -v15, v88, v14
	v_cndmask_b32_e64 v85, v85, v86, s[0:1]
	v_sqrt_f32_e32 v86, v85
	v_fmac_f32_e32 v88, v89, v90
	v_fma_f32 v14, -v15, v88, v14
	s_nop 1
	v_mov_b32_dpp v91, v87 quad_perm:[2,3,0,1] row_mask:0xf bank_mask:0xf
	v_add_u32_e32 v15, -1, v86
	v_fma_f32 v89, -v15, v86, v85
	v_cmp_ge_f32_e64 s[4:5], 0, v89
	v_add_u32_e32 v89, 1, v86
	v_fmac_f32_e32 v84, v58, v58
	v_cndmask_b32_e64 v15, v86, v15, s[4:5]
	v_fma_f32 v86, -v89, v86, v85
	v_cmp_lt_f32_e64 s[4:5], 0, v86
	v_fmac_f32_e32 v84, v30, v30
	v_div_fmas_f32 v14, v14, v90, v88
	v_cndmask_b32_e64 v15, v15, v89, s[4:5]
	v_mul_f32_e32 v86, 0x37800000, v15
	v_cndmask_b32_e64 v15, v15, v86, s[0:1]
	s_waitcnt lgkmcnt(0)
	v_add_f32_e32 v86, v87, v91
	s_nop 1
	v_mov_b32_dpp v87, v86 row_half_mirror row_mask:0xf bank_mask:0xf
	v_cmp_class_f32_e64 s[0:1], v85, v175
	v_div_fixup_f32 v13, v14, v13, s74
	s_nop 1
	v_mov_b32_dpp v91, v84 quad_perm:[1,0,3,2] row_mask:0xf bank_mask:0xf
	v_cndmask_b32_e64 v15, v15, v85, s[0:1]
	s_waitcnt lgkmcnt(1)
	v_add_f32_e32 v86, v86, v87
	s_nop 1
	v_mov_b32_dpp v87, v86 row_mirror row_mask:0xf bank_mask:0xf
	v_div_scale_f32 v85, s[0:1], v15, v15, s74
	v_rcp_f32_e32 v89, v85
	s_waitcnt lgkmcnt(1)
	v_add_f32_e32 v84, v84, v91
	s_waitcnt lgkmcnt(0)
	v_add_f32_e32 v86, v86, v87
	v_mov_b32_e32 v87, v86
	v_mov_b32_e32 v228, v86
	s_nop 1
	v_permlane16_swap_b32_e32 v87, v228
	s_nop 1
	v_cndmask_b32_e64 v87, v87, v228, s[98:99]
	v_fma_f32 v14, -v85, v89, 1.0
	v_fmac_f32_e32 v89, v14, v89
	v_div_scale_f32 v14, vcc, s74, v15, s74
	s_waitcnt lgkmcnt(0)
	v_add_f32_e32 v86, v86, v87
	v_fmamk_f32 v86, v86, 0x3c000000, v165
	v_mul_f32_e32 v87, 0x4f800000, v86
	v_cmp_gt_f32_e64 s[0:1], s73, v86
	v_mul_f32_e32 v88, v14, v89
	v_fma_f32 v90, -v85, v88, v14
	v_cndmask_b32_e64 v86, v86, v87, s[0:1]
	v_sqrt_f32_e32 v87, v86
	v_fmac_f32_e32 v88, v90, v89
	v_fma_f32 v14, -v85, v88, v14
	s_nop 1
	v_mov_b32_dpp v91, v84 quad_perm:[2,3,0,1] row_mask:0xf bank_mask:0xf
	v_add_u32_e32 v85, -1, v87
	v_fma_f32 v90, -v85, v87, v86
	v_cmp_ge_f32_e64 s[4:5], 0, v90
	v_add_u32_e32 v90, 1, v87
	s_waitcnt lgkmcnt(0)
	v_add_f32_e32 v84, v84, v91
	v_cndmask_b32_e64 v85, v87, v85, s[4:5]
	v_fma_f32 v87, -v90, v87, v86
	v_cmp_lt_f32_e64 s[4:5], 0, v87
	v_mul_f32_e32 v83, v35, v35
	v_fmac_f32_e32 v83, v66, v66
	v_cndmask_b32_e64 v85, v85, v90, s[4:5]
	v_mul_f32_e32 v87, 0x37800000, v85
	v_cndmask_b32_e64 v85, v85, v87, s[0:1]
	s_nop 1
	v_mov_b32_dpp v87, v84 row_half_mirror row_mask:0xf bank_mask:0xf
	v_cmp_class_f32_e64 s[0:1], v86, v175
	v_fmac_f32_e32 v83, v18, v18
	v_fmac_f32_e32 v83, v2, v2
	v_cndmask_b32_e64 v85, v85, v86, s[0:1]
	s_waitcnt lgkmcnt(0)
	v_add_f32_e32 v84, v84, v87
	s_nop 1
	v_mov_b32_dpp v87, v84 row_mirror row_mask:0xf bank_mask:0xf
	v_div_scale_f32 v86, s[0:1], v85, v85, s74
	v_rcp_f32_e32 v90, v86
	v_div_fmas_f32 v14, v14, v89, v88
	s_waitcnt lgkmcnt(0)
	v_add_f32_e32 v84, v84, v87
	v_mov_b32_e32 v87, v84
	v_mov_b32_e32 v228, v84
	s_nop 1
	v_permlane16_swap_b32_e32 v87, v228
	s_nop 1
	v_cndmask_b32_e64 v87, v87, v228, s[98:99]
	v_div_fixup_f32 v14, v14, v15, s74
	v_fma_f32 v15, -v86, v90, 1.0
	s_nop 1
	v_mov_b32_dpp v91, v83 quad_perm:[1,0,3,2] row_mask:0xf bank_mask:0xf
	v_fmac_f32_e32 v90, v15, v90
	s_waitcnt lgkmcnt(1)
; __device__ __forceinline__ float bf_lo(unsigned w) { return __uint_as_float(w << 16); }
; __device__ __forceinline__ float bf_hi(unsigned w) { return __uint_as_float(w & 0xffff0000u); }
;     ...
;         for (int r = 0; r < 16; r += 2) { const unsigned w = stash[(d0 * 8 + (r >> 1)) * 64];
;           const float a0 = bf_lo(w) - lam * (o[d0][r] * rli[r]), a1 = bf_hi(w) - lam * (o[d0][r + 1] * rli[r + 1]);
;           o[d0][r] = a0; o[d0][r + 1] = a1; ss[r] += a0 * a0; ss[r + 1] += a1 * a1; }
; #pragma unroll
;       for (int r = 0; r < 16; ++r) { float s = ss[r];
;         s += __shfl_xor(s, 1); s += __shfl_xor(s, 2); s += __shfl_xor(s, 4); s += __shfl_xor(s, 8); s += __shfl_xor(s, 16);
;         ss[r] = (1.0f - LAM_INIT) / sqrtf(s * (1.0f / 128.0f) + EPS); }
	v_add_f32_e32 v84, v84, v87
	v_fmamk_f32 v84, v84, 0x3c000000, v165
	v_mul_f32_e32 v87, 0x4f800000, v84
	v_cmp_gt_f32_e64 s[0:1], s73, v84
	v_div_scale_f32 v15, vcc, s74, v85, s74
	s_nop 0
	v_cndmask_b32_e64 v84, v84, v87, s[0:1]
	v_sqrt_f32_e32 v87, v84
	v_mul_f32_e32 v88, v15, v90
	v_fma_f32 v89, -v86, v88, v15
	v_fmac_f32_e32 v88, v89, v90
	v_fma_f32 v15, -v86, v88, v15
	v_add_u32_e32 v86, -1, v87
	s_waitcnt lgkmcnt(0)
	v_add_f32_e32 v83, v83, v91
	v_fma_f32 v89, -v86, v87, v84
	s_nop 1
	v_mov_b32_dpp v91, v83 quad_perm:[2,3,0,1] row_mask:0xf bank_mask:0xf
	v_cmp_ge_f32_e64 s[4:5], 0, v89
	v_add_u32_e32 v89, 1, v87
	v_mul_f32_e32 v72, v38, v38
	v_cndmask_b32_e64 v86, v87, v86, s[4:5]
	v_fma_f32 v87, -v89, v87, v84
	v_cmp_lt_f32_e64 s[4:5], 0, v87
	s_waitcnt lgkmcnt(0)
	v_add_f32_e32 v83, v83, v91
	v_fmac_f32_e32 v72, v65, v65
	v_cndmask_b32_e64 v86, v86, v89, s[4:5]
	v_mul_f32_e32 v87, 0x37800000, v86
	v_cndmask_b32_e64 v86, v86, v87, s[0:1]
	s_nop 1
	v_mov_b32_dpp v87, v83 row_half_mirror row_mask:0xf bank_mask:0xf
	v_cmp_class_f32_e64 s[0:1], v84, v175
	v_fmac_f32_e32 v72, v59, v59
	v_fmac_f32_e32 v72, v31, v31
	v_cndmask_b32_e64 v84, v86, v84, s[0:1]
	s_waitcnt lgkmcnt(0)
	v_add_f32_e32 v83, v83, v87
	s_nop 1
	v_mov_b32_dpp v87, v83 row_mirror row_mask:0xf bank_mask:0xf
	v_div_scale_f32 v86, s[0:1], v84, v84, s74
	v_rcp_f32_e32 v89, v86
	v_div_fmas_f32 v15, v15, v90, v88
	s_waitcnt lgkmcnt(0)
	v_add_f32_e32 v83, v83, v87
	v_mov_b32_e32 v87, v83
	v_mov_b32_e32 v228, v83
	s_nop 1
	v_permlane16_swap_b32_e32 v87, v228
	s_nop 1
	v_cndmask_b32_e64 v87, v87, v228, s[98:99]
	v_div_fixup_f32 v15, v15, v85, s74
	v_fma_f32 v85, -v86, v89, 1.0
	s_nop 1
	v_mov_b32_dpp v91, v72 quad_perm:[1,0,3,2] row_mask:0xf bank_mask:0xf
	v_fmac_f32_e32 v89, v85, v89
	s_waitcnt lgkmcnt(1)
	v_add_f32_e32 v83, v83, v87
	v_fmamk_f32 v83, v83, 0x3c000000, v165
	v_mul_f32_e32 v87, 0x4f800000, v83
	v_cmp_gt_f32_e64 s[0:1], s73, v83
	v_div_scale_f32 v85, vcc, s74, v84, s74
	s_nop 0
	v_cndmask_b32_e64 v83, v83, v87, s[0:1]
	v_sqrt_f32_e32 v87, v83
	v_mul_f32_e32 v88, v85, v89
	v_fma_f32 v90, -v86, v88, v85
	v_fmac_f32_e32 v88, v90, v89
	v_fma_f32 v85, -v86, v88, v85
	v_add_u32_e32 v86, -1, v87
	s_waitcnt lgkmcnt(0)
	v_add_f32_e32 v72, v72, v91
	v_fma_f32 v90, -v86, v87, v83
	s_nop 1
	v_mov_b32_dpp v91, v72 quad_perm:[2,3,0,1] row_mask:0xf bank_mask:0xf
	v_cmp_ge_f32_e64 s[4:5], 0, v90
	v_add_u32_e32 v90, 1, v87
	v_mul_f32_e32 v75, v37, v37
	v_cndmask_b32_e64 v86, v87, v86, s[4:5]
	v_fma_f32 v87, -v90, v87, v83
	v_cmp_lt_f32_e64 s[4:5], 0, v87
	s_waitcnt lgkmcnt(0)
	v_add_f32_e32 v72, v72, v91
	v_fmac_f32_e32 v75, v64, v64
	v_cndmask_b32_e64 v86, v86, v90, s[4:5]
	v_mul_f32_e32 v87, 0x37800000, v86
	v_cndmask_b32_e64 v86, v86, v87, s[0:1]
	s_nop 1
	v_mov_b32_dpp v87, v72 row_half_mirror row_mask:0xf bank_mask:0xf
	v_cmp_class_f32_e64 s[0:1], v83, v175
	v_fmac_f32_e32 v75, v19, v19
	v_fmac_f32_e32 v75, v3, v3
	v_cndmask_b32_e64 v83, v86, v83, s[0:1]
	s_waitcnt lgkmcnt(0)
	v_add_f32_e32 v87, v72, v87
	s_nop 1
	v_mov_b32_dpp v91, v87 row_mirror row_mask:0xf bank_mask:0xf
	v_div_fmas_f32 v72, v85, v89, v88
	v_div_scale_f32 v86, s[0:1], v83, v83, s74
	v_rcp_f32_e32 v90, v86
	s_waitcnt lgkmcnt(0)
	v_add_f32_e32 v85, v87, v91
	v_mov_b32_e32 v87, v85
	v_mov_b32_e32 v228, v85
	s_nop 1
	v_permlane16_swap_b32_e32 v87, v228
	s_nop 1
	v_cndmask_b32_e64 v87, v87, v228, s[98:99]
	v_div_fixup_f32 v72, v72, v84, s74
	v_fma_f32 v84, -v86, v90, 1.0
	s_nop 1
	v_mov_b32_dpp v91, v75 quad_perm:[1,0,3,2] row_mask:0xf bank_mask:0xf
	v_fmac_f32_e32 v90, v84, v90
	s_waitcnt lgkmcnt(1)
	v_add_f32_e32 v85, v85, v87
	v_fmamk_f32 v85, v85, 0x3c000000, v165
	v_mul_f32_e32 v87, 0x4f800000, v85
	v_cmp_gt_f32_e64 s[0:1], s73, v85
	v_div_scale_f32 v84, vcc, s74, v83, s74
	s_nop 0
	v_cndmask_b32_e64 v85, v85, v87, s[0:1]
	v_sqrt_f32_e32 v87, v85
	v_mul_f32_e32 v88, v84, v90
	v_fma_f32 v89, -v86, v88, v84
	v_fmac_f32_e32 v88, v89, v90
	v_fma_f32 v84, -v86, v88, v84
	v_add_u32_e32 v86, -1, v87
	s_waitcnt lgkmcnt(0)
	v_add_f32_e32 v75, v75, v91
	v_fma_f32 v89, -v86, v87, v85
	s_nop 1
	v_mov_b32_dpp v91, v75 quad_perm:[2,3,0,1] row_mask:0xf bank_mask:0xf
	v_cmp_ge_f32_e64 s[4:5], 0, v89
	v_add_u32_e32 v89, 1, v87
	v_mul_f32_e32 v81, v40, v40
	v_cndmask_b32_e64 v86, v87, v86, s[4:5]
	v_fma_f32 v87, -v89, v87, v85
	v_cmp_lt_f32_e64 s[4:5], 0, v87
	s_waitcnt lgkmcnt(0)
	v_add_f32_e32 v75, v75, v91
	v_fmac_f32_e32 v81, v55, v55
	v_cndmask_b32_e64 v86, v86, v89, s[4:5]
	v_mul_f32_e32 v87, 0x37800000, v86
	v_cndmask_b32_e64 v86, v86, v87, s[0:1]
	s_nop 1
	v_mov_b32_dpp v87, v75 row_half_mirror row_mask:0xf bank_mask:0xf
	v_cmp_class_f32_e64 s[0:1], v85, v175
	v_fmac_f32_e32 v81, v23, v23
	v_fmac_f32_e32 v81, v7, v7
	v_cndmask_b32_e64 v85, v86, v85, s[0:1]
	s_waitcnt lgkmcnt(0)
	v_add_f32_e32 v87, v75, v87
	s_nop 1
	v_mov_b32_dpp v91, v87 row_mirror row_mask:0xf bank_mask:0xf
	v_div_fmas_f32 v75, v84, v90, v88
	v_div_scale_f32 v86, s[0:1], v85, v85, s74
	v_rcp_f32_e32 v89, v86
	s_waitcnt lgkmcnt(0)
	v_add_f32_e32 v84, v87, v91
	v_mov_b32_e32 v87, v84
	v_mov_b32_e32 v228, v84
	s_nop 1
	v_permlane16_swap_b32_e32 v87, v228
	s_nop 1
	v_cndmask_b32_e64 v87, v87, v228, s[98:99]
	v_div_fixup_f32 v75, v75, v83, s74
	v_fma_f32 v83, -v86, v89, 1.0
	s_nop 1
	v_mov_b32_dpp v91, v81 quad_perm:[1,0,3,2] row_mask:0xf bank_mask:0xf
	v_fmac_f32_e32 v89, v83, v89
	s_waitcnt lgkmcnt(1)
	v_add_f32_e32 v84, v84, v87
	v_fmamk_f32 v84, v84, 0x3c000000, v165
	v_mul_f32_e32 v87, 0x4f800000, v84
	v_cmp_gt_f32_e64 s[0:1], s73, v84
	v_div_scale_f32 v83, vcc, s74, v85, s74
	s_nop 0
	v_cndmask_b32_e64 v84, v84, v87, s[0:1]
	v_sqrt_f32_e32 v87, v84
	v_mul_f32_e32 v88, v83, v89
	v_fma_f32 v90, -v86, v88, v83
	v_fmac_f32_e32 v88, v90, v89
	v_fma_f32 v83, -v86, v88, v83
	v_add_u32_e32 v86, -1, v87
	s_waitcnt lgkmcnt(0)
; __device__ __forceinline__ float bf_lo(unsigned w) { return __uint_as_float(w << 16); }
; __device__ __forceinline__ float bf_hi(unsigned w) { return __uint_as_float(w & 0xffff0000u); }
;     ...
;         for (int r = 0; r < 16; r += 2) { const unsigned w = stash[(d0 * 8 + (r >> 1)) * 64];
;           const float a0 = bf_lo(w) - lam * (o[d0][r] * rli[r]), a1 = bf_hi(w) - lam * (o[d0][r + 1] * rli[r + 1]);
;           o[d0][r] = a0; o[d0][r + 1] = a1; ss[r] += a0 * a0; ss[r + 1] += a1 * a1; }
; #pragma unroll
;       for (int r = 0; r < 16; ++r) { float s = ss[r];
;         s += __shfl_xor(s, 1); s += __shfl_xor(s, 2); s += __shfl_xor(s, 4); s += __shfl_xor(s, 8); s += __shfl_xor(s, 16);
;         ss[r] = (1.0f - LAM_INIT) / sqrtf(s * (1.0f / 128.0f) + EPS); }
	v_add_f32_e32 v81, v81, v91
	v_fma_f32 v90, -v86, v87, v84
	s_nop 1
	v_mov_b32_dpp v91, v81 quad_perm:[2,3,0,1] row_mask:0xf bank_mask:0xf
	v_cmp_ge_f32_e64 s[4:5], 0, v90
	v_add_u32_e32 v90, 1, v87
	v_mul_f32_e32 v82, v39, v39
	v_cndmask_b32_e64 v86, v87, v86, s[4:5]
	v_fma_f32 v87, -v90, v87, v84
	v_cmp_lt_f32_e64 s[4:5], 0, v87
	s_waitcnt lgkmcnt(0)
	v_add_f32_e32 v81, v81, v91
	v_fmac_f32_e32 v82, v54, v54
	v_cndmask_b32_e64 v86, v86, v90, s[4:5]
	v_mul_f32_e32 v87, 0x37800000, v86
	v_cndmask_b32_e64 v86, v86, v87, s[0:1]
	s_nop 1
	v_mov_b32_dpp v87, v81 row_half_mirror row_mask:0xf bank_mask:0xf
	v_cmp_class_f32_e64 s[0:1], v84, v175
	v_fmac_f32_e32 v82, v20, v20
	v_fmac_f32_e32 v82, v4, v4
	v_cndmask_b32_e64 v84, v86, v84, s[0:1]
	s_waitcnt lgkmcnt(0)
	v_add_f32_e32 v87, v81, v87
	s_nop 1
	v_mov_b32_dpp v91, v87 row_mirror row_mask:0xf bank_mask:0xf
	v_div_fmas_f32 v81, v83, v89, v88
	v_div_fixup_f32 v81, v81, v85, s74
	v_div_scale_f32 v86, s[0:1], v84, v84, s74
	s_waitcnt lgkmcnt(0)
	v_add_f32_e32 v85, v87, v91
	v_mov_b32_e32 v87, v85
	v_mov_b32_e32 v228, v85
	s_nop 1
	v_permlane16_swap_b32_e32 v87, v228
	s_nop 1
	v_cndmask_b32_e64 v87, v87, v228, s[98:99]
	v_rcp_f32_e32 v90, v86
	s_nop 1
	v_mov_b32_dpp v91, v82 quad_perm:[1,0,3,2] row_mask:0xf bank_mask:0xf
	v_mul_f32_e32 v80, v42, v42
	v_fmac_f32_e32 v80, v53, v53
	s_waitcnt lgkmcnt(1)
	v_add_f32_e32 v85, v85, v87
	v_fmamk_f32 v85, v85, 0x3c000000, v165
	v_mul_f32_e32 v87, 0x4f800000, v85
	v_cmp_gt_f32_e64 s[0:1], s73, v85
	v_fma_f32 v83, -v86, v90, 1.0
	v_fmac_f32_e32 v90, v83, v90
	v_cndmask_b32_e64 v85, v85, v87, s[0:1]
	v_div_scale_f32 v83, vcc, s74, v84, s74
	v_sqrt_f32_e32 v87, v85
	v_mul_f32_e32 v88, v83, v90
	v_fma_f32 v89, -v86, v88, v83
	v_fmac_f32_e32 v88, v89, v90
	v_fma_f32 v83, -v86, v88, v83
	v_add_u32_e32 v86, -1, v87
	s_waitcnt lgkmcnt(0)
	v_add_f32_e32 v82, v82, v91
	v_fma_f32 v89, -v86, v87, v85
	s_nop 1
	v_mov_b32_dpp v91, v82 quad_perm:[2,3,0,1] row_mask:0xf bank_mask:0xf
	v_cmp_ge_f32_e64 s[4:5], 0, v89
	v_add_u32_e32 v89, 1, v87
	v_fmac_f32_e32 v80, v24, v24
	v_cndmask_b32_e64 v86, v87, v86, s[4:5]
	v_fma_f32 v87, -v89, v87, v85
	v_cmp_lt_f32_e64 s[4:5], 0, v87
	s_waitcnt lgkmcnt(0)
	v_add_f32_e32 v82, v82, v91
	v_fmac_f32_e32 v80, v8, v8
	v_cndmask_b32_e64 v86, v86, v89, s[4:5]
	v_mul_f32_e32 v87, 0x37800000, v86
	v_cndmask_b32_e64 v86, v86, v87, s[0:1]
	s_nop 1
	v_mov_b32_dpp v87, v82 row_half_mirror row_mask:0xf bank_mask:0xf
	v_cmp_class_f32_e64 s[0:1], v85, v175
	v_mul_f32_e32 v74, v41, v41
	v_fmac_f32_e32 v74, v52, v52
	v_cndmask_b32_e64 v85, v86, v85, s[0:1]
	s_waitcnt lgkmcnt(0)
	v_add_f32_e32 v87, v82, v87
	s_nop 1
	v_mov_b32_dpp v91, v87 row_mirror row_mask:0xf bank_mask:0xf
	v_div_fmas_f32 v82, v83, v90, v88
	v_div_fixup_f32 v82, v82, v84, s74
	v_div_scale_f32 v86, s[0:1], v85, v85, s74
	s_waitcnt lgkmcnt(0)
	v_add_f32_e32 v84, v87, v91
	v_mov_b32_e32 v87, v84
	v_mov_b32_e32 v228, v84
	s_nop 1
	v_permlane16_swap_b32_e32 v87, v228
	s_nop 1
	v_cndmask_b32_e64 v87, v87, v228, s[98:99]
	v_rcp_f32_e32 v89, v86
	s_nop 1
	v_mov_b32_dpp v91, v80 quad_perm:[1,0,3,2] row_mask:0xf bank_mask:0xf
	v_fmac_f32_e32 v74, v21, v21
	v_fmac_f32_e32 v74, v5, v5
	s_waitcnt lgkmcnt(1)
	v_add_f32_e32 v84, v84, v87
	v_fmamk_f32 v84, v84, 0x3c000000, v165
	v_mul_f32_e32 v87, 0x4f800000, v84
	v_cmp_gt_f32_e64 s[0:1], s73, v84
	v_fma_f32 v83, -v86, v89, 1.0
	v_fmac_f32_e32 v89, v83, v89
	v_cndmask_b32_e64 v84, v84, v87, s[0:1]
	v_div_scale_f32 v83, vcc, s74, v85, s74
	v_sqrt_f32_e32 v87, v84
	v_mul_f32_e32 v88, v83, v89
	v_fma_f32 v90, -v86, v88, v83
	v_fmac_f32_e32 v88, v90, v89
	v_fma_f32 v83, -v86, v88, v83
	v_add_u32_e32 v86, -1, v87
	s_waitcnt lgkmcnt(0)
	v_add_f32_e32 v80, v80, v91
	v_fma_f32 v90, -v86, v87, v84
	s_nop 1
	v_mov_b32_dpp v91, v80 quad_perm:[2,3,0,1] row_mask:0xf bank_mask:0xf
	v_cmp_ge_f32_e64 s[4:5], 0, v90
	v_add_u32_e32 v90, 1, v87
	v_mul_f32_e32 v63, v44, v44
	v_cndmask_b32_e64 v86, v87, v86, s[4:5]
	v_fma_f32 v87, -v90, v87, v84
	v_cmp_lt_f32_e64 s[4:5], 0, v87
	s_waitcnt lgkmcnt(0)
	v_add_f32_e32 v80, v80, v91
	v_fmac_f32_e32 v63, v51, v51
	v_cndmask_b32_e64 v86, v86, v90, s[4:5]
	v_mul_f32_e32 v87, 0x37800000, v86
	v_cndmask_b32_e64 v86, v86, v87, s[0:1]
	s_nop 1
	v_mov_b32_dpp v87, v80 row_half_mirror row_mask:0xf bank_mask:0xf
	v_cmp_class_f32_e64 s[0:1], v84, v175
	v_fmac_f32_e32 v63, v25, v25
	v_fmac_f32_e32 v63, v9, v9
	v_cndmask_b32_e64 v84, v86, v84, s[0:1]
	s_waitcnt lgkmcnt(0)
	v_add_f32_e32 v87, v80, v87
	s_nop 1
	v_mov_b32_dpp v91, v87 row_mirror row_mask:0xf bank_mask:0xf
	v_div_fmas_f32 v80, v83, v89, v88
	v_div_fixup_f32 v80, v80, v85, s74
	v_div_scale_f32 v86, s[0:1], v84, v84, s74
	s_waitcnt lgkmcnt(0)
	v_add_f32_e32 v85, v87, v91
	v_mov_b32_e32 v87, v85
	v_mov_b32_e32 v228, v85
	s_nop 1
	v_permlane16_swap_b32_e32 v87, v228
	s_nop 1
	v_cndmask_b32_e64 v87, v87, v228, s[98:99]
	v_rcp_f32_e32 v90, v86
	s_nop 1
	v_mov_b32_dpp v91, v74 quad_perm:[1,0,3,2] row_mask:0xf bank_mask:0xf
	v_mul_f32_e32 v62, v43, v43
	v_fmac_f32_e32 v62, v49, v49
	s_waitcnt lgkmcnt(1)
	v_add_f32_e32 v85, v85, v87
	v_fmamk_f32 v85, v85, 0x3c000000, v165
	v_mul_f32_e32 v87, 0x4f800000, v85
	v_cmp_gt_f32_e64 s[0:1], s73, v85
	v_fma_f32 v83, -v86, v90, 1.0
	v_fmac_f32_e32 v90, v83, v90
	v_cndmask_b32_e64 v85, v85, v87, s[0:1]
	v_div_scale_f32 v83, vcc, s74, v84, s74
	v_sqrt_f32_e32 v87, v85
	v_mul_f32_e32 v88, v83, v90
	v_fma_f32 v89, -v86, v88, v83
	v_fmac_f32_e32 v88, v89, v90
	v_fma_f32 v83, -v86, v88, v83
	v_add_u32_e32 v86, -1, v87
	s_waitcnt lgkmcnt(0)
; __device__ __forceinline__ float bf_lo(unsigned w) { return __uint_as_float(w << 16); }
; __device__ __forceinline__ float bf_hi(unsigned w) { return __uint_as_float(w & 0xffff0000u); }
;     ...
;         for (int r = 0; r < 16; r += 2) { const unsigned w = stash[(d0 * 8 + (r >> 1)) * 64];
;           const float a0 = bf_lo(w) - lam * (o[d0][r] * rli[r]), a1 = bf_hi(w) - lam * (o[d0][r + 1] * rli[r + 1]);
;           o[d0][r] = a0; o[d0][r + 1] = a1; ss[r] += a0 * a0; ss[r + 1] += a1 * a1; }
; #pragma unroll
;       for (int r = 0; r < 16; ++r) { float s = ss[r];
;         s += __shfl_xor(s, 1); s += __shfl_xor(s, 2); s += __shfl_xor(s, 4); s += __shfl_xor(s, 8); s += __shfl_xor(s, 16);
;         ss[r] = (1.0f - LAM_INIT) / sqrtf(s * (1.0f / 128.0f) + EPS); }
	v_add_f32_e32 v74, v74, v91
	v_fma_f32 v89, -v86, v87, v85
	s_nop 1
	v_mov_b32_dpp v91, v74 quad_perm:[2,3,0,1] row_mask:0xf bank_mask:0xf
	v_cmp_ge_f32_e64 s[4:5], 0, v89
	v_add_u32_e32 v89, 1, v87
	v_fmac_f32_e32 v62, v22, v22
	v_cndmask_b32_e64 v86, v87, v86, s[4:5]
	v_fma_f32 v87, -v89, v87, v85
	v_cmp_lt_f32_e64 s[4:5], 0, v87
	s_waitcnt lgkmcnt(0)
	v_add_f32_e32 v74, v74, v91
	v_fmac_f32_e32 v62, v6, v6
	v_cndmask_b32_e64 v86, v86, v89, s[4:5]
	v_mul_f32_e32 v87, 0x37800000, v86
	v_cndmask_b32_e64 v86, v86, v87, s[0:1]
	s_nop 1
	v_mov_b32_dpp v87, v74 row_half_mirror row_mask:0xf bank_mask:0xf
	v_cmp_class_f32_e64 s[0:1], v85, v175
	v_mul_f32_e32 v61, v46, v46
	v_fmac_f32_e32 v61, v48, v48
	v_cndmask_b32_e64 v85, v86, v85, s[0:1]
	s_waitcnt lgkmcnt(0)
	v_add_f32_e32 v87, v74, v87
	s_nop 1
	v_mov_b32_dpp v91, v87 row_mirror row_mask:0xf bank_mask:0xf
	v_div_fmas_f32 v74, v83, v90, v88
	v_div_fixup_f32 v74, v74, v84, s74
	v_div_scale_f32 v86, s[0:1], v85, v85, s74
	s_waitcnt lgkmcnt(0)
	v_add_f32_e32 v84, v87, v91
	v_mov_b32_e32 v87, v84
	v_mov_b32_e32 v228, v84
	s_nop 1
	v_permlane16_swap_b32_e32 v87, v228
	s_nop 1
	v_cndmask_b32_e64 v87, v87, v228, s[98:99]
	v_rcp_f32_e32 v89, v86
	s_nop 1
	v_mov_b32_dpp v91, v63 quad_perm:[1,0,3,2] row_mask:0xf bank_mask:0xf
	v_fmac_f32_e32 v61, v27, v27
	v_fmac_f32_e32 v61, v10, v10
	s_waitcnt lgkmcnt(1)
	v_add_f32_e32 v84, v84, v87
	v_fmamk_f32 v84, v84, 0x3c000000, v165
	v_mul_f32_e32 v87, 0x4f800000, v84
	v_cmp_gt_f32_e64 s[0:1], s73, v84
	v_fma_f32 v83, -v86, v89, 1.0
	v_fmac_f32_e32 v89, v83, v89
	v_cndmask_b32_e64 v84, v84, v87, s[0:1]
	v_div_scale_f32 v83, vcc, s74, v85, s74
	v_sqrt_f32_e32 v87, v84
	v_mul_f32_e32 v88, v83, v89
	v_fma_f32 v90, -v86, v88, v83
	v_fmac_f32_e32 v88, v90, v89
	v_fma_f32 v83, -v86, v88, v83
	v_add_u32_e32 v86, -1, v87
	s_waitcnt lgkmcnt(0)
	v_add_f32_e32 v63, v63, v91
	v_fma_f32 v90, -v86, v87, v84
	s_nop 1
	v_mov_b32_dpp v91, v63 quad_perm:[2,3,0,1] row_mask:0xf bank_mask:0xf
	v_cmp_ge_f32_e64 s[4:5], 0, v90
	v_add_u32_e32 v90, 1, v87
	v_mul_f32_e32 v60, v45, v45
	v_cndmask_b32_e64 v86, v87, v86, s[4:5]
	v_fma_f32 v87, -v90, v87, v84
	v_cmp_lt_f32_e64 s[4:5], 0, v87
	s_waitcnt lgkmcnt(0)
	v_add_f32_e32 v63, v63, v91
	v_fmac_f32_e32 v60, v50, v50
	v_cndmask_b32_e64 v86, v86, v90, s[4:5]
	v_mul_f32_e32 v87, 0x37800000, v86
	v_cndmask_b32_e64 v86, v86, v87, s[0:1]
	s_nop 1
	v_mov_b32_dpp v87, v63 row_half_mirror row_mask:0xf bank_mask:0xf
	v_cmp_class_f32_e64 s[0:1], v84, v175
	v_fmac_f32_e32 v60, v26, v26
	v_fmac_f32_e32 v60, v11, v11
	v_cndmask_b32_e64 v84, v86, v84, s[0:1]
	s_waitcnt lgkmcnt(0)
	v_add_f32_e32 v87, v63, v87
	s_nop 1
	v_mov_b32_dpp v91, v87 row_mirror row_mask:0xf bank_mask:0xf
	v_div_fmas_f32 v63, v83, v89, v88
	v_div_fixup_f32 v63, v63, v85, s74
	v_div_scale_f32 v86, s[0:1], v84, v84, s74
	s_waitcnt lgkmcnt(0)
	v_add_f32_e32 v85, v87, v91
	v_mov_b32_e32 v87, v85
	v_mov_b32_e32 v228, v85
	s_nop 1
	v_permlane16_swap_b32_e32 v87, v228
	s_nop 1
	v_cndmask_b32_e64 v87, v87, v228, s[98:99]
	v_rcp_f32_e32 v90, v86
	s_nop 1
	v_mov_b32_dpp v91, v62 quad_perm:[1,0,3,2] row_mask:0xf bank_mask:0xf
	v_mul_f32_e32 v32, v32, v13
	v_mul_f32_e32 v0, v0, v13
	s_waitcnt lgkmcnt(1)
	v_add_f32_e32 v85, v85, v87
	v_fmamk_f32 v85, v85, 0x3c000000, v165
	v_mul_f32_e32 v87, 0x4f800000, v85
	v_cmp_gt_f32_e64 s[0:1], s73, v85
	v_fma_f32 v83, -v86, v90, 1.0
	v_fmac_f32_e32 v90, v83, v90
	v_cndmask_b32_e64 v85, v85, v87, s[0:1]
	v_div_scale_f32 v83, vcc, s74, v84, s74
	v_sqrt_f32_e32 v87, v85
	v_mul_f32_e32 v88, v83, v90
	v_fma_f32 v89, -v86, v88, v83
	v_fmac_f32_e32 v88, v89, v90
	v_fma_f32 v83, -v86, v88, v83
	v_add_u32_e32 v86, -1, v87
	s_waitcnt lgkmcnt(0)
	v_add_f32_e32 v62, v62, v91
	v_fma_f32 v89, -v86, v87, v85
	s_nop 1
	v_mov_b32_dpp v91, v62 quad_perm:[2,3,0,1] row_mask:0xf bank_mask:0xf
	v_cmp_ge_f32_e64 s[4:5], 0, v89
	v_add_u32_e32 v89, 1, v87
	v_mul_f32_e32 v16, v16, v13
	v_cndmask_b32_e64 v86, v87, v86, s[4:5]
	v_fma_f32 v87, -v89, v87, v85
	v_cmp_lt_f32_e64 s[4:5], 0, v87
	s_waitcnt lgkmcnt(0)
	v_add_f32_e32 v62, v62, v91
	v_mul_f32_e32 v71, v71, v12
	v_cndmask_b32_e64 v86, v86, v89, s[4:5]
	v_mul_f32_e32 v87, 0x37800000, v86
	v_cndmask_b32_e64 v86, v86, v87, s[0:1]
	s_nop 1
	v_mov_b32_dpp v87, v62 row_half_mirror row_mask:0xf bank_mask:0xf
	v_cmp_class_f32_e64 s[0:1], v85, v175
	v_mul_f32_e32 v70, v70, v13
	v_mul_f32_e32 v69, v69, v14
	v_cndmask_b32_e64 v85, v86, v85, s[0:1]
	s_waitcnt lgkmcnt(0)
	v_add_f32_e32 v87, v62, v87
	s_nop 1
	v_mov_b32_dpp v91, v87 row_mirror row_mask:0xf bank_mask:0xf
	v_div_fmas_f32 v62, v83, v90, v88
	v_div_fixup_f32 v62, v62, v84, s74
	v_div_scale_f32 v86, s[0:1], v85, v85, s74
	s_waitcnt lgkmcnt(0)
	v_add_f32_e32 v84, v87, v91
	v_mov_b32_e32 v87, v84
	v_mov_b32_e32 v228, v84
	s_nop 1
	v_permlane16_swap_b32_e32 v87, v228
	s_nop 1
	v_cndmask_b32_e64 v87, v87, v228, s[98:99]
	v_rcp_f32_e32 v89, v86
	s_nop 1
	v_mov_b32_dpp v91, v61 quad_perm:[1,0,3,2] row_mask:0xf bank_mask:0xf
	s_nop 1
	v_mov_b32_dpp v73, v60 quad_perm:[1,0,3,2] row_mask:0xf bank_mask:0xf
	v_mul_f32_e32 v68, v68, v15
	s_waitcnt lgkmcnt(2)
	v_add_f32_e32 v84, v84, v87
	v_fmamk_f32 v84, v84, 0x3c000000, v165
	v_mul_f32_e32 v87, 0x4f800000, v84
	v_cmp_gt_f32_e64 s[0:1], s73, v84
	v_fma_f32 v83, -v86, v89, 1.0
	v_fmac_f32_e32 v89, v83, v89
	v_cndmask_b32_e64 v84, v84, v87, s[0:1]
	v_div_scale_f32 v83, vcc, s74, v85, s74
	v_sqrt_f32_e32 v87, v84
	v_mul_f32_e32 v88, v83, v89
	v_fma_f32 v90, -v86, v88, v83
	v_fmac_f32_e32 v88, v90, v89
	v_fma_f32 v83, -v86, v88, v83
	v_add_u32_e32 v86, -1, v87
	s_waitcnt lgkmcnt(1)
; __device__ __forceinline__ unsigned cvt_pk_bf16(float lo, float hi) { f32x2 v = {lo, hi}; bf16x2_t b = __builtin_convertvector(v, bf16x2_t); return __builtin_bit_cast(unsigned, b); }
; __device__ __forceinline__ int crow(int r, int hi) { return (r & 3) + 8 * (r >> 2) + 4 * hi; }
;     ...
;       for (int r = 0; r < 16; ++r) { float s = ss[r];
;         s += __shfl_xor(s, 1); s += __shfl_xor(s, 2); s += __shfl_xor(s, 4); s += __shfl_xor(s, 8); s += __shfl_xor(s, 16);
;         ss[r] = (1.0f - LAM_INIT) / sqrtf(s * (1.0f / 128.0f) + EPS); }
;       bf16_t* stg = (bf16_t*)(lds + OFF_ST) + wid * 4096;
; #pragma unroll
;       for (int d0 = 0; d0 < 4; ++d0) { const float g = subln_g[d0 * 32 + r32];
; #pragma unroll
;         for (int r = 0; r < 16; ++r) { const unsigned w = cvt_pk_bf16(o[d0][r] * ss[r] * g, 0.f);
;           stg[crow(r, hi) * 128 + d0 * 32 + r32] = (bf16_t)(w & 0xffffu); } }
	v_add_f32_e32 v61, v61, v91
	v_fma_f32 v90, -v86, v87, v84
	s_nop 1
	v_mov_b32_dpp v91, v61 quad_perm:[2,3,0,1] row_mask:0xf bank_mask:0xf
	v_cmp_ge_f32_e64 s[4:5], 0, v90
	v_add_u32_e32 v90, 1, v87
	s_waitcnt lgkmcnt(1)
	v_add_f32_e32 v60, v60, v73
	v_cndmask_b32_e64 v86, v87, v86, s[4:5]
	v_fma_f32 v87, -v90, v87, v84
	v_cmp_lt_f32_e64 s[4:5], 0, v87
	s_waitcnt lgkmcnt(0)
	v_add_f32_e32 v61, v61, v91
	s_nop 1
	v_mov_b32_dpp v73, v60 quad_perm:[2,3,0,1] row_mask:0xf bank_mask:0xf
	v_cndmask_b32_e64 v86, v86, v90, s[4:5]
	v_mul_f32_e32 v87, 0x37800000, v86
	v_cndmask_b32_e64 v86, v86, v87, s[0:1]
	s_nop 1
	v_mov_b32_dpp v87, v61 row_half_mirror row_mask:0xf bank_mask:0xf
	v_cmp_class_f32_e64 s[0:1], v84, v175
	s_waitcnt lgkmcnt(1)
	v_add_f32_e32 v60, v60, v73
	s_nop 1
	v_mov_b32_dpp v73, v60 row_half_mirror row_mask:0xf bank_mask:0xf
	v_cndmask_b32_e64 v84, v86, v84, s[0:1]
	s_waitcnt lgkmcnt(1)
	v_add_f32_e32 v87, v61, v87
	s_nop 1
	v_mov_b32_dpp v91, v87 row_mirror row_mask:0xf bank_mask:0xf
	v_div_fmas_f32 v61, v83, v89, v88
	v_div_fixup_f32 v61, v61, v85, s74
	v_div_scale_f32 v86, s[0:1], v84, v84, s74
	s_waitcnt lgkmcnt(0)
	v_add_f32_e32 v85, v87, v91
	v_mov_b32_e32 v87, v85
	v_mov_b32_e32 v228, v85
	s_nop 1
	v_permlane16_swap_b32_e32 v87, v228
	s_nop 1
	v_cndmask_b32_e64 v87, v87, v228, s[98:99]
	v_rcp_f32_e32 v90, v86
	v_add_f32_e32 v60, v60, v73
	s_nop 1
	v_mov_b32_dpp v73, v60 row_mirror row_mask:0xf bank_mask:0xf
	v_lshlrev_b32_e32 v89, 2, v178
	s_waitcnt lgkmcnt(1)
	v_add_f32_e32 v85, v85, v87
	v_fmamk_f32 v85, v85, 0x3c000000, v165
	v_mul_f32_e32 v87, 0x4f800000, v85
	v_cmp_gt_f32_e64 s[0:1], s73, v85
	v_fma_f32 v83, -v86, v90, 1.0
	v_fmac_f32_e32 v90, v83, v90
	v_cndmask_b32_e64 v85, v85, v87, s[0:1]
	v_div_scale_f32 v83, vcc, s74, v84, s74
	v_sqrt_f32_e32 v87, v85
	v_mul_f32_e32 v88, v83, v90
	v_fma_f32 v92, -v86, v88, v83
	v_fmac_f32_e32 v88, v92, v90
	v_fma_f32 v83, -v86, v88, v83
	v_add_u32_e32 v86, -1, v87
	v_fma_f32 v92, -v86, v87, v85
	v_cmp_ge_f32_e64 s[4:5], 0, v92
	v_add_u32_e32 v92, 1, v87
	s_waitcnt lgkmcnt(0)
	v_add_f32_e32 v60, v60, v73
	v_cndmask_b32_e64 v86, v87, v86, s[4:5]
	v_fma_f32 v87, -v92, v87, v85
	v_cmp_lt_f32_e64 s[4:5], 0, v87
	v_mov_b32_e32 v73, v60
	v_mov_b32_e32 v228, v60
	s_nop 1
	v_permlane16_swap_b32_e32 v73, v228
	s_nop 1
	v_cndmask_b32_e64 v73, v73, v228, s[98:99]
	v_div_fmas_f32 v78, v83, v90, v88
	v_cndmask_b32_e64 v76, v86, v92, s[4:5]
	v_mul_f32_e32 v86, 0x37800000, v76
	v_cndmask_b32_e64 v76, v76, v86, s[0:1]
	v_cmp_class_f32_e64 s[0:1], v85, v175
	s_waitcnt lgkmcnt(0)
	v_add_f32_e32 v60, v60, v73
	v_fmamk_f32 v60, v60, 0x3c000000, v165
	v_cndmask_b32_e64 v76, v76, v85, s[0:1]
	v_div_scale_f32 v77, s[0:1], v76, v76, s74
	v_rcp_f32_e32 v85, v77
	v_mul_f32_e32 v73, 0x4f800000, v60
	v_cmp_gt_f32_e64 s[0:1], s73, v60
	v_div_scale_f32 v79, vcc, s74, v76, s74
	v_fma_f32 v83, -v77, v85, 1.0
	v_cndmask_b32_e64 v60, v60, v73, s[0:1]
	v_fmac_f32_e32 v85, v83, v85
	v_sqrt_f32_e32 v73, v60
	v_mul_f32_e32 v83, v79, v85
	v_div_fixup_f32 v78, v78, v84, s74
	v_fma_f32 v84, -v77, v83, v79
	v_fmac_f32_e32 v83, v84, v85
	v_fma_f32 v77, -v77, v83, v79
	v_add_u32_e32 v79, -1, v73
	v_fma_f32 v84, -v79, v73, v60
	v_cmp_ge_f32_e64 s[4:5], 0, v84
	v_add_u32_e32 v84, 1, v73
	v_div_fmas_f32 v77, v77, v85, v83
	v_cndmask_b32_e64 v79, v73, v79, s[4:5]
	v_fma_f32 v73, -v84, v73, v60
	v_cmp_lt_f32_e64 s[4:5], 0, v73
	v_div_fixup_f32 v76, v77, v76, s74
	global_load_dword v91, v89, s[56:57]
	global_load_dword v83, v89, s[56:57] offset:128
	v_cndmask_b32_e64 v73, v79, v84, s[4:5]
	v_mul_f32_e32 v79, 0x37800000, v73
	v_cndmask_b32_e64 v73, v73, v79, s[0:1]
	v_cmp_class_f32_e64 s[0:1], v60, v175
	v_mul_f32_e32 v48, v48, v76
	v_mul_f32_e32 v67, v67, v72
	v_cndmask_b32_e64 v60, v73, v60, s[0:1]
	v_div_scale_f32 v73, s[0:1], v60, v60, s74
	v_rcp_f32_e32 v79, v73
	v_mul_f32_e32 v66, v66, v75
	v_mul_f32_e32 v65, v65, v81
	v_mul_f32_e32 v64, v64, v82
	v_fma_f32 v77, -v73, v79, 1.0
	v_fmac_f32_e32 v79, v77, v79
	v_div_scale_f32 v77, vcc, s74, v60, s74
	v_mul_f32_e32 v84, v77, v79
	v_fma_f32 v85, -v73, v84, v77
	v_fmac_f32_e32 v84, v85, v79
	v_fma_f32 v73, -v73, v84, v77
	v_div_fmas_f32 v73, v73, v79, v84
	global_load_dword v77, v89, s[56:57] offset:256
	global_load_dword v79, v89, s[56:57] offset:384
	v_div_fixup_f32 v60, v73, v60, s74
	v_lshlrev_b32_e32 v73, 1, v178
	v_add3_u32 v73, s18, v179, v73
	v_mul_f32_e32 v55, v55, v80
	v_mul_f32_e32 v54, v54, v74
	v_mul_f32_e32 v53, v53, v63
	v_mul_f32_e32 v52, v52, v62
	v_mul_f32_e32 v51, v51, v61
	v_mul_f32_e32 v49, v49, v78
	s_waitcnt vmcnt(3)
	v_mul_f32_e32 v48, v91, v48
	s_waitcnt vmcnt(2)
	v_mul_f32_e32 v32, v32, v83
	v_cvt_pk_bf16_f32 v32, v32, s0
	ds_write_b16 v73, v32 offset:320
	v_mul_f32_e32 v32, v34, v14
	v_mul_f32_e32 v32, v32, v83
	v_cvt_pk_bf16_f32 v32, v32, s0
	ds_write_b16 v73, v32 offset:576
	v_mul_f32_e32 v32, v33, v15
	v_mul_f32_e32 v32, v32, v83
	v_cvt_pk_bf16_f32 v32, v32, s0
	ds_write_b16 v73, v32 offset:832
	v_mul_f32_e32 v32, v36, v72
	v_mul_f32_e32 v32, v32, v83
	v_cvt_pk_bf16_f32 v32, v32, s0
	ds_write_b16 v73, v32 offset:2112
	v_mul_f32_e32 v32, v35, v75
	v_mul_f32_e32 v32, v32, v83
	v_cvt_pk_bf16_f32 v32, v32, s0
	ds_write_b16 v73, v32 offset:2368
	v_mul_f32_e32 v32, v38, v81
	v_mul_f32_e32 v32, v32, v83
	v_cvt_pk_bf16_f32 v32, v32, s0
	s_waitcnt vmcnt(1)
	v_mul_f32_e32 v16, v16, v77
	s_waitcnt vmcnt(0)
; __device__ __forceinline__ unsigned cvt_pk_bf16(float lo, float hi) { f32x2 v = {lo, hi}; bf16x2_t b = __builtin_convertvector(v, bf16x2_t); return __builtin_bit_cast(unsigned, b); }
; __device__ __forceinline__ int crow(int r, int hi) { return (r & 3) + 8 * (r >> 2) + 4 * hi; }
;     ...
;       for (int d0 = 0; d0 < 4; ++d0) { const float g = subln_g[d0 * 32 + r32];
; #pragma unroll
;         for (int r = 0; r < 16; ++r) { const unsigned w = cvt_pk_bf16(o[d0][r] * ss[r] * g, 0.f);
;           stg[crow(r, hi) * 128 + d0 * 32 + r32] = (bf16_t)(w & 0xffffu); } }
	v_mul_f32_e32 v0, v0, v79
	v_cvt_pk_bf16_f32 v0, v0, s0
	v_cvt_pk_bf16_f32 v16, v16, s0
	ds_write_b16 v73, v0 offset:448
	v_mul_f32_e32 v0, v29, v14
	ds_write_b16 v73, v16 offset:384
	v_mul_f32_e32 v16, v57, v14
	v_mul_f32_e32 v0, v0, v79
	v_mul_f32_e32 v16, v16, v77
	v_cvt_pk_bf16_f32 v0, v0, s0
	v_cvt_pk_bf16_f32 v16, v16, s0
	ds_write_b16 v73, v0 offset:704
	v_mul_f32_e32 v0, v1, v15
	ds_write_b16 v73, v16 offset:640
	v_mul_f32_e32 v16, v17, v15
	v_mul_f32_e32 v0, v0, v79
	v_mul_f32_e32 v16, v16, v77
	v_cvt_pk_bf16_f32 v0, v0, s0
	v_cvt_pk_bf16_f32 v16, v16, s0
	ds_write_b16 v73, v0 offset:960
	v_mul_f32_e32 v0, v30, v72
	ds_write_b16 v73, v16 offset:896
	v_mul_f32_e32 v16, v58, v72
	v_mul_f32_e32 v0, v0, v79
	v_mul_f32_e32 v16, v16, v77
	v_cvt_pk_bf16_f32 v0, v0, s0
	v_cvt_pk_bf16_f32 v16, v16, s0
	ds_write_b16 v73, v0 offset:2240
	v_mul_f32_e32 v0, v2, v75
	ds_write_b16 v73, v16 offset:2176
	v_mul_f32_e32 v16, v18, v75
	v_mul_f32_e32 v0, v0, v79
	v_mul_f32_e32 v16, v16, v77
	v_cvt_pk_bf16_f32 v0, v0, s0
	v_cvt_pk_bf16_f32 v16, v16, s0
	ds_write_b16 v73, v0 offset:2496
	v_mul_f32_e32 v0, v31, v81
	ds_write_b16 v73, v32 offset:2624
	v_mul_f32_e32 v32, v37, v82
	ds_write_b16 v73, v16 offset:2432
	v_mul_f32_e32 v16, v59, v81
	v_mul_f32_e32 v0, v0, v79
	v_mul_f32_e32 v32, v32, v83
	v_mul_f32_e32 v16, v16, v77
	v_cvt_pk_bf16_f32 v0, v0, s0
	v_cvt_pk_bf16_f32 v32, v32, s0
	v_cvt_pk_bf16_f32 v16, v16, s0
	ds_write_b16 v73, v0 offset:2752
	v_mul_f32_e32 v0, v3, v82
	ds_write_b16 v73, v32 offset:2880
	v_mul_f32_e32 v32, v40, v80
	ds_write_b16 v73, v16 offset:2688
	v_mul_f32_e32 v16, v19, v82
	v_mul_f32_e32 v0, v0, v79
	v_mul_f32_e32 v32, v32, v83
	v_mul_f32_e32 v16, v16, v77
	v_cvt_pk_bf16_f32 v0, v0, s0
	v_cvt_pk_bf16_f32 v32, v32, s0
	v_cvt_pk_bf16_f32 v16, v16, s0
	ds_write_b16 v73, v0 offset:3008
	v_mul_f32_e32 v0, v7, v80
	ds_write_b16 v73, v32 offset:4160
	v_mul_f32_e32 v32, v39, v74
	ds_write_b16 v73, v16 offset:2944
	v_mul_f32_e32 v16, v23, v80
	v_mul_f32_e32 v0, v0, v79
	v_mul_f32_e32 v32, v32, v83
	v_mul_f32_e32 v16, v16, v77
	v_cvt_pk_bf16_f32 v0, v0, s0
	v_cvt_pk_bf16_f32 v32, v32, s0
	v_cvt_pk_bf16_f32 v16, v16, s0
	ds_write_b16 v73, v0 offset:4288
	v_mul_f32_e32 v0, v4, v74
	ds_write_b16 v73, v32 offset:4416
	v_mul_f32_e32 v32, v42, v63
	ds_write_b16 v73, v16 offset:4224
	v_mul_f32_e32 v16, v20, v74
	v_mul_f32_e32 v0, v0, v79
	v_mul_f32_e32 v32, v32, v83
	v_mul_f32_e32 v16, v16, v77
	v_cvt_pk_bf16_f32 v0, v0, s0
	v_cvt_pk_bf16_f32 v32, v32, s0
	v_cvt_pk_bf16_f32 v16, v16, s0
	ds_write_b16 v73, v0 offset:4544
	v_mul_f32_e32 v0, v8, v63
	ds_write_b16 v73, v32 offset:4672
	v_mul_f32_e32 v32, v41, v62
	ds_write_b16 v73, v16 offset:4480
	v_mul_f32_e32 v16, v24, v63
	v_mul_f32_e32 v0, v0, v79
	v_mul_f32_e32 v32, v32, v83
	v_mul_f32_e32 v16, v16, v77
	v_cvt_pk_bf16_f32 v0, v0, s0
	v_cvt_pk_bf16_f32 v32, v32, s0
	v_cvt_pk_bf16_f32 v16, v16, s0
	ds_write_b16 v73, v0 offset:4800
	v_mul_f32_e32 v0, v5, v62
	ds_write_b16 v73, v32 offset:4928
	v_mul_f32_e32 v32, v44, v61
	ds_write_b16 v73, v16 offset:4736
	v_mul_f32_e32 v16, v21, v62
	v_mul_f32_e32 v0, v0, v79
	v_mul_f32_e32 v32, v32, v83
	v_mul_f32_e32 v16, v16, v77
	v_cvt_pk_bf16_f32 v0, v0, s0
	v_cvt_pk_bf16_f32 v32, v32, s0
	v_cvt_pk_bf16_f32 v16, v16, s0
	ds_write_b16 v73, v0 offset:5056
	v_mul_f32_e32 v0, v9, v61
	ds_write_b16 v73, v32 offset:6208
	v_mul_f32_e32 v32, v43, v78
	ds_write_b16 v73, v16 offset:4992
	v_mul_f32_e32 v16, v25, v61
	v_mul_f32_e32 v0, v0, v79
	v_mul_f32_e32 v32, v32, v83
	v_mul_f32_e32 v16, v16, v77
	v_cvt_pk_bf16_f32 v0, v0, s0
	v_cvt_pk_bf16_f32 v32, v32, s0
	v_cvt_pk_bf16_f32 v16, v16, s0
	ds_write_b16 v73, v0 offset:6336
	v_mul_f32_e32 v0, v6, v78
	ds_write_b16 v73, v32 offset:6464
	v_mul_f32_e32 v32, v46, v76
	ds_write_b16 v73, v16 offset:6272
	v_mul_f32_e32 v16, v22, v78
	v_mul_f32_e32 v0, v0, v79
	v_mul_f32_e32 v32, v32, v83
	v_mul_f32_e32 v16, v16, v77
	v_cvt_pk_bf16_f32 v0, v0, s0
	v_cvt_pk_bf16_f32 v48, v48, s0
	v_cvt_pk_bf16_f32 v32, v32, s0
	v_cvt_pk_bf16_f32 v16, v16, s0
	ds_write_b16 v73, v0 offset:6592
	v_mul_f32_e32 v0, v10, v76
	ds_write_b16 v73, v48 offset:6656
	v_mul_f32_e32 v48, v50, v60
	ds_write_b16 v73, v32 offset:6720
	v_mul_f32_e32 v32, v45, v60
	ds_write_b16 v73, v16 offset:6528
	v_mul_f32_e32 v16, v27, v76
	v_mul_f32_e32 v0, v0, v79
	v_mul_f32_e32 v48, v91, v48
	v_mul_f32_e32 v32, v32, v83
	v_mul_f32_e32 v16, v16, v77
	v_cvt_pk_bf16_f32 v0, v0, s0
	v_cvt_pk_bf16_f32 v48, v48, s0
	v_cvt_pk_bf16_f32 v32, v32, s0
	v_cvt_pk_bf16_f32 v16, v16, s0
	ds_write_b16 v73, v0 offset:6848
	v_mul_f32_e32 v0, v11, v60
	ds_write_b16 v73, v48 offset:6912
	v_mul_f32_e32 v48, v56, v12
	ds_write_b16 v73, v32 offset:6976
	v_mul_f32_e32 v32, v47, v12
	ds_write_b16 v73, v16 offset:6784
	v_mul_f32_e32 v16, v26, v60
	v_mul_f32_e32 v12, v28, v12
	v_mul_f32_e32 v0, v0, v79
	v_mul_f32_e32 v71, v71, v91
	v_mul_f32_e32 v70, v70, v91
	v_mul_f32_e32 v69, v69, v91
	v_mul_f32_e32 v68, v68, v91
	v_mul_f32_e32 v67, v67, v91
	v_mul_f32_e32 v66, v66, v91
	v_mul_f32_e32 v65, v65, v91
	v_mul_f32_e32 v64, v64, v91
	v_mul_f32_e32 v55, v55, v91
	v_mul_f32_e32 v54, v54, v91
	v_mul_f32_e32 v53, v53, v91
	v_mul_f32_e32 v52, v52, v91
	v_mul_f32_e32 v51, v51, v91
	v_mul_f32_e32 v49, v49, v91
	v_mul_f32_e32 v48, v48, v83
	v_mul_f32_e32 v32, v32, v77
	v_mul_f32_e32 v16, v16, v77
	v_mul_f32_e32 v12, v12, v79
	v_cvt_pk_bf16_f32 v0, v0, s0
	v_cvt_pk_bf16_f32 v71, v71, s0
	v_cvt_pk_bf16_f32 v70, v70, s0
	v_cvt_pk_bf16_f32 v69, v69, s0
	v_cvt_pk_bf16_f32 v68, v68, s0
	v_cvt_pk_bf16_f32 v67, v67, s0
	v_cvt_pk_bf16_f32 v66, v66, s0
	v_cvt_pk_bf16_f32 v65, v65, s0
	v_cvt_pk_bf16_f32 v64, v64, s0
	v_cvt_pk_bf16_f32 v55, v55, s0
	v_cvt_pk_bf16_f32 v54, v54, s0
	v_cvt_pk_bf16_f32 v53, v53, s0
	v_cvt_pk_bf16_f32 v52, v52, s0
	v_cvt_pk_bf16_f32 v51, v51, s0
	v_cvt_pk_bf16_f32 v49, v49, s0
	v_cvt_pk_bf16_f32 v48, v48, s0
	v_cvt_pk_bf16_f32 v32, v32, s0
	v_cvt_pk_bf16_f32 v16, v16, s0
	v_cvt_pk_bf16_f32 v12, v12, s0
	ds_write_b16 v73, v0 offset:7104
	v_lshrrev_b32_e32 v4, 4, v169
	v_lshlrev_b32_e32 v0, 1, v177
	ds_write_b16 v73, v71
	ds_write_b16 v73, v70 offset:256
	ds_write_b16 v73, v69 offset:512
	ds_write_b16 v73, v68 offset:768
	ds_write_b16 v73, v67 offset:2048
	ds_write_b16 v73, v66 offset:2304
	ds_write_b16 v73, v65 offset:2560
	ds_write_b16 v73, v64 offset:2816
	ds_write_b16 v73, v55 offset:4096
	ds_write_b16 v73, v54 offset:4352
	ds_write_b16 v73, v53 offset:4608
	ds_write_b16 v73, v52 offset:4864
	ds_write_b16 v73, v51 offset:6144
	ds_write_b16 v73, v49 offset:6400
	ds_write_b16 v73, v48 offset:64
	ds_write_b16 v73, v32 offset:128
	ds_write_b16 v73, v16 offset:7040
	ds_write_b16 v73, v12 offset:192
	v_and_b32_e32 v5, 0xf0, v0
	v_lshlrev_b32_e32 v0, 8, v4
	s_waitcnt lgkmcnt(0)
;     ...
;       asm volatile("s_waitcnt lgkmcnt(0)" ::: "memory");
;       const char* ob = (const char*)(O + qrow0 * LD + h * 128);
;       const unsigned lo = (unsigned)((lane >> 4) * LD + (lane & 15) * 8) * 2u;
; #pragma unroll
;       for (int i = 0; i < 8; ++i) { const u32x4 v = *(const u32x4*)(stg + (i * 4 + (lane >> 4)) * 128 + (lane & 15) * 8); *(u32x4*)((char*)ob + lo) = v; ob += 4 * LD * 2; }
;     }
;     __syncthreads();
; __global__ void __launch_bounds__(NTHREADS) fwd_megakernel(Args a) {
;     ...
;         for (int u = vcu; u < NB * 8 * (SEQ / 256); u += G) {
	s_lshl_b64 s[0:1], s[14:15], 11
	v_add3_u32 v12, s18, v0, v5
	s_add_u32 s0, s21, s0
	ds_read_b128 v[0:3], v12
	s_addc_u32 s1, s82, s1
	s_add_u32 s0, s0, s6
	v_lshl_or_b32 v166, v4, 11, v5
	ds_read_b128 v[4:7], v12 offset:1024
	s_addc_u32 s1, s1, 0
	v_lshl_add_u64 v[8:9], s[0:1], 0, v[166:167]
	s_waitcnt lgkmcnt(1)
	global_store_dwordx4 v166, v[0:3], s[0:1]
	s_movk_i32 s0, 0x4000
	s_add_i32 s2, s2, s90
	v_add_co_u32_e32 v0, vcc, s75, v8
	s_add_i32 s23, s23, s46
	s_nop 0
	v_addc_co_u32_e32 v1, vcc, 0, v9, vcc
	s_waitcnt lgkmcnt(0)
	global_store_dwordx4 v[0:1], v[4:7], off
	ds_read_b128 v[0:3], v12 offset:2048
	ds_read_b128 v[4:7], v12 offset:3072
	v_add_co_u32_e32 v10, vcc, s0, v8
	s_mov_b32 s0, 0xc000
	s_nop 0
	v_addc_co_u32_e32 v11, vcc, 0, v9, vcc
	s_waitcnt lgkmcnt(1)
	global_store_dwordx4 v[10:11], v[0:3], off
	s_cmpk_gt_i32 s2, 0x1ff
	s_nop 0
	v_add_co_u32_e32 v0, vcc, 0x6000, v8
	s_nop 1
	v_addc_co_u32_e32 v1, vcc, 0, v9, vcc
	s_waitcnt lgkmcnt(0)
	global_store_dwordx4 v[0:1], v[4:7], off
	ds_read_b128 v[0:3], v12 offset:4096
	ds_read_b128 v[4:7], v12 offset:5120
	v_add_co_u32_e32 v10, vcc, 0x8000, v8
	s_nop 1
	v_addc_co_u32_e32 v11, vcc, 0, v9, vcc
	s_waitcnt lgkmcnt(1)
	global_store_dwordx4 v[10:11], v[0:3], off
	s_nop 1
	v_add_co_u32_e32 v0, vcc, 0xa000, v8
	s_nop 1
	v_addc_co_u32_e32 v1, vcc, 0, v9, vcc
	s_waitcnt lgkmcnt(0)
	global_store_dwordx4 v[0:1], v[4:7], off
	ds_read_b128 v[0:3], v12 offset:6144
	ds_read_b128 v[4:7], v12 offset:7168
	v_add_co_u32_e32 v10, vcc, s0, v8
	s_nop 1
	v_addc_co_u32_e32 v11, vcc, 0, v9, vcc
	s_waitcnt lgkmcnt(1)
	global_store_dwordx4 v[10:11], v[0:3], off
	s_nop 1
	v_add_co_u32_e32 v0, vcc, 0xe000, v8
	s_nop 1
	v_addc_co_u32_e32 v1, vcc, 0, v9, vcc
	s_waitcnt lgkmcnt(0)
	global_store_dwordx4 v[0:1], v[4:7], off
	s_barrier
	s_cbranch_scc1 .LBB0_745
